# prep cache conversion loops: next iteration load kept in flight (2-way unrolled)
# speedup vs baseline: 1.0017x; 1.0017x over previous
.Lcv777_top0:
	v_ashrrev_i32_e32 v0, 31, v7
	v_lshrrev_b32_e32 v0, 16, v0
	v_lshl_add_u64 v[14:15], v[6:7], 0, v[0:1]
	v_ashrrev_i64 v[14:15], 16, v[14:15]
	v_mov_b32_e32 v12, v1
	v_lshl_add_u64 v[6:7], v[6:7], 0, s[46:47]
	s_mov_b64 s[8:9], 0x7ffff
	v_mov_b32_e32 v13, v14
	v_cmp_lt_i64_e32 vcc, s[8:9], v[6:7]
	v_mad_i64_i32 v[14:15], s[8:9], v14, s52, 0
	v_ashrrev_i64 v[12:13], 13, v[12:13]
	s_or_b64 s[6:7], vcc, s[6:7]
	v_sub_co_u32_e32 v12, vcc, v14, v12
	v_lshl_add_u64 v[4:5], v[4:5], 0, s[48:49]
	s_nop 0
	v_subb_co_u32_e32 v13, vcc, v15, v13, vcc
	v_lshl_add_u64 v[12:13], v[2:3], 0, v[12:13]
	v_lshl_add_u64 v[2:3], v[2:3], 0, s[50:51]
	s_mov_b64 s[64:65], exec
	s_andn2_b64 exec, exec, s[6:7]
	s_cbranch_execz .Lcv777_np0
	global_load_dwordx4 v[100:103], v[4:5], off offset:-8
	s_mov_b64 exec, s[64:65]
	s_waitcnt vmcnt(1)
	s_branch .Lcv777_go0
.Lcv777_np0:
	s_mov_b64 exec, s[64:65]
	s_waitcnt vmcnt(0)
.Lcv777_go0:
	v_cvt_pk_bf16_f32 v104, v8, v9
	v_cvt_pk_bf16_f32 v105, v10, v11
	global_store_dwordx2 v[12:13], v[104:105], off
	s_andn2_b64 exec, exec, s[6:7]
	s_cbranch_execz .Lcv777_done
.Lcv777_top1:
	v_ashrrev_i32_e32 v0, 31, v7
	v_lshrrev_b32_e32 v0, 16, v0
	v_lshl_add_u64 v[14:15], v[6:7], 0, v[0:1]
	v_ashrrev_i64 v[14:15], 16, v[14:15]
	v_mov_b32_e32 v12, v1
	v_lshl_add_u64 v[6:7], v[6:7], 0, s[46:47]
	s_mov_b64 s[8:9], 0x7ffff
	v_mov_b32_e32 v13, v14
	v_cmp_lt_i64_e32 vcc, s[8:9], v[6:7]
	v_mad_i64_i32 v[14:15], s[8:9], v14, s52, 0
	v_ashrrev_i64 v[12:13], 13, v[12:13]
	s_or_b64 s[6:7], vcc, s[6:7]
	v_sub_co_u32_e32 v12, vcc, v14, v12
	v_lshl_add_u64 v[4:5], v[4:5], 0, s[48:49]
	s_nop 0
	v_subb_co_u32_e32 v13, vcc, v15, v13, vcc
	v_lshl_add_u64 v[12:13], v[2:3], 0, v[12:13]
	v_lshl_add_u64 v[2:3], v[2:3], 0, s[50:51]
	s_mov_b64 s[64:65], exec
	s_andn2_b64 exec, exec, s[6:7]
	s_cbranch_execz .Lcv777_np1
	global_load_dwordx4 v[8:11], v[4:5], off offset:-8
	s_mov_b64 exec, s[64:65]
	s_waitcnt vmcnt(1)
	s_branch .Lcv777_go1

.Lcv777_go1:
	v_cvt_pk_bf16_f32 v104, v100, v101
	v_cvt_pk_bf16_f32 v105, v102, v103
	global_store_dwordx2 v[12:13], v[104:105], off
	s_andn2_b64 exec, exec, s[6:7]
	s_cbranch_execnz .Lcv777_top0
.Lcv777_done:
.LBB0_778:
	s_or_b64 exec, exec, s[4:5]
	s_mov_b64 s[4:5], 0x20000
	v_cmp_gt_i64_e32 vcc, s[4:5], v[66:67]
	s_and_saveexec_b64 s[4:5], vcc
	v_readlane_b32 s14, v253, 2
	v_readlane_b32 s46, v253, 25
	v_readlane_b32 s48, v253, 31
	v_readlane_b32 s15, v253, 3
	v_readlane_b32 s47, v253, 26
	v_readlane_b32 s49, v253, 32
	s_mov_b32 s50, 0x21000
	s_cbranch_execz .LBB0_781
	v_readlane_b32 s6, v254, 7
	v_readlane_b32 s7, v254, 8
	s_load_dwordx2 s[6:7], s[6:7], 0x108
	v_readlane_b32 s0, v253, 33
	s_waitcnt vmcnt(0)
	v_mov_b64_e32 v[6:7], v[66:67]
	s_waitcnt lgkmcnt(0)
	s_add_u32 s6, s6, s0
	v_readlane_b32 s0, v253, 34
	s_addc_u32 s7, s7, s0
	v_lshl_add_u64 v[2:3], v[216:217], 3, s[6:7]
	v_readlane_b32 s6, v253, 29
	v_readlane_b32 s7, v253, 30
	s_add_u32 s0, s10, s6
	s_addc_u32 s7, s11, s7
	s_add_u32 s6, s0, s44
	s_addc_u32 s7, s7, s45
	v_lshl_add_u64 v[4:5], v[216:217], 4, s[6:7]
	s_mov_b64 s[6:7], 0

.Lcv783_top0:
	v_ashrrev_i32_e32 v0, 31, v7
	v_lshrrev_b32_e32 v0, 14, v0
	v_lshl_add_u64 v[14:15], v[6:7], 0, v[0:1]
	v_ashrrev_i64 v[14:15], 18, v[14:15]
	v_mov_b32_e32 v12, v1
	v_lshl_add_u64 v[6:7], v[6:7], 0, s[10:11]
	s_mov_b64 s[8:9], 0x1fffff
	v_mov_b32_e32 v13, v14
	v_cmp_lt_i64_e32 vcc, s[8:9], v[6:7]
	v_mad_i64_i32 v[14:15], s[8:9], v14, s46, 0
	v_ashrrev_i64 v[12:13], 11, v[12:13]
	s_or_b64 s[6:7], vcc, s[6:7]
	v_sub_co_u32_e32 v12, vcc, v14, v12
	v_lshl_add_u64 v[4:5], v[4:5], 0, s[14:15]
	s_nop 0
	v_subb_co_u32_e32 v13, vcc, v15, v13, vcc
	v_lshl_add_u64 v[12:13], v[2:3], 0, v[12:13]
	v_lshl_add_u64 v[2:3], v[2:3], 0, s[44:45]
	s_mov_b64 s[64:65], exec
	s_andn2_b64 exec, exec, s[6:7]
	s_cbranch_execz .Lcv783_np0
	global_load_dwordx4 v[100:103], v[4:5], off offset:-8
	s_mov_b64 exec, s[64:65]
	s_waitcnt vmcnt(1)
	s_branch .Lcv783_go0

.Lcv783_top1:
	v_ashrrev_i32_e32 v0, 31, v7
	v_lshrrev_b32_e32 v0, 14, v0
	v_lshl_add_u64 v[14:15], v[6:7], 0, v[0:1]
	v_ashrrev_i64 v[14:15], 18, v[14:15]
	v_mov_b32_e32 v12, v1
	v_lshl_add_u64 v[6:7], v[6:7], 0, s[10:11]
	s_mov_b64 s[8:9], 0x1fffff
	v_mov_b32_e32 v13, v14
	v_cmp_lt_i64_e32 vcc, s[8:9], v[6:7]
	v_mad_i64_i32 v[14:15], s[8:9], v14, s46, 0
	v_ashrrev_i64 v[12:13], 11, v[12:13]
	s_or_b64 s[6:7], vcc, s[6:7]
	v_sub_co_u32_e32 v12, vcc, v14, v12
	v_lshl_add_u64 v[4:5], v[4:5], 0, s[14:15]
	s_nop 0
	v_subb_co_u32_e32 v13, vcc, v15, v13, vcc
	v_lshl_add_u64 v[12:13], v[2:3], 0, v[12:13]
	v_lshl_add_u64 v[2:3], v[2:3], 0, s[44:45]
	s_mov_b64 s[64:65], exec
	s_andn2_b64 exec, exec, s[6:7]
	s_cbranch_execz .Lcv783_np1
	global_load_dwordx4 v[8:11], v[4:5], off offset:-8
	s_mov_b64 exec, s[64:65]
	s_waitcnt vmcnt(1)
	s_branch .Lcv783_go1

.Lcv783_done:
.LBB0_784:
	s_or_b64 exec, exec, s[4:5]
	s_mov_b64 s[4:5], 0xc000
	v_cmp_gt_i64_e64 s[10:11], s[4:5], v[66:67]
	v_readlane_b32 s4, v253, 4
	v_readlane_b32 s5, v253, 5
	s_nop 1
	v_lshl_add_u64 v[2:3], s[4:5], 0, v[216:217]
	s_and_saveexec_b64 s[8:9], s[10:11]
	v_readlane_b32 s6, v253, 2
	v_readlane_b32 s7, v253, 3
	s_cbranch_execz .LBB0_796
	s_mov_b64 s[4:5], 0xc000
	v_cmp_lt_i64_e32 vcc, s[4:5], v[2:3]
	v_mov_b32_e32 v4, 0xc000
	v_cmp_gt_i64_e64 s[4:5], s[4:5], v[2:3]
	v_cndmask_b32_e32 v4, v4, v2, vcc
	v_cndmask_b32_e32 v0, 0, v3, vcc
	v_cndmask_b32_e64 v5, 0, 1, s[4:5]
	v_sub_co_u32_e32 v4, vcc, v4, v5
	s_nop 1
	v_subbrev_co_u32_e32 v0, vcc, 0, v0, vcc
	s_waitcnt vmcnt(0)
	v_sub_co_u32_e32 v6, vcc, v4, v2
	v_mov_b32_e32 v4, v1
	s_nop 0
	v_subb_co_u32_e32 v7, vcc, v0, v3, vcc
	v_or_b32_e32 v5, s7, v7
	v_cmp_ne_u64_e32 vcc, 0, v[4:5]
	s_and_saveexec_b64 s[6:7], vcc
	s_xor_b64 s[12:13], exec, s[6:7]
	s_cbranch_execz .LBB0_787
	v_readlane_b32 s50, v253, 2
	v_readlane_b32 s51, v253, 3
	s_sub_u32 s0, 0, s50
	v_cvt_f32_u32_e32 v0, s50
	v_cvt_f32_u32_e32 v4, s51
	s_subb_u32 s14, 0, s51
	v_fmac_f32_e32 v0, 0x4f800000, v4
	v_rcp_f32_e32 v0, v0
	s_nop 0
	v_mul_f32_e32 v0, 0x5f7ffffc, v0
	v_mul_f32_e32 v4, 0x2f800000, v0
	v_trunc_f32_e32 v4, v4
	v_fmac_f32_e32 v0, 0xcf800000, v4
	v_cvt_u32_f32_e32 v4, v4
	v_cvt_u32_f32_e32 v0, v0
	v_readfirstlane_b32 s15, v4
	v_readfirstlane_b32 s6, v0
	s_mul_i32 s7, s0, s15
	s_mul_hi_u32 s45, s0, s6
	s_mul_i32 s44, s14, s6
	s_add_i32 s7, s45, s7
	s_mul_i32 s46, s0, s6
	s_add_i32 s7, s7, s44
	s_mul_i32 s45, s6, s7
	s_mul_hi_u32 s47, s6, s46
	s_mul_hi_u32 s44, s6, s7
	s_add_u32 s45, s47, s45
	s_addc_u32 s44, 0, s44
	s_mul_hi_u32 s48, s15, s46
	s_mul_i32 s46, s15, s46
	s_add_u32 s45, s45, s46
	s_mul_hi_u32 s47, s15, s7
	s_addc_u32 s44, s44, s48
	s_addc_u32 s45, s47, 0
	s_mul_i32 s7, s15, s7
	s_add_u32 s7, s44, s7
	s_addc_u32 s44, 0, s45
	s_add_u32 s45, s6, s7
	s_cselect_b64 s[6:7], -1, 0
	s_cmp_lg_u64 s[6:7], 0
	s_addc_u32 s15, s15, s44
	s_mul_i32 s6, s0, s15
	s_mul_hi_u32 s7, s0, s45
	s_add_i32 s6, s7, s6
	s_mul_i32 s14, s14, s45
	s_add_i32 s6, s6, s14
	s_mul_i32 s0, s0, s45
	s_mul_hi_u32 s14, s15, s0
	s_mul_i32 s44, s15, s0
	s_mul_i32 s47, s45, s6
	s_mul_hi_u32 s0, s45, s0
	s_mul_hi_u32 s46, s45, s6
	s_add_u32 s0, s0, s47
	s_addc_u32 s46, 0, s46
	s_add_u32 s0, s0, s44
	s_mul_hi_u32 s7, s15, s6
	s_addc_u32 s0, s46, s14
	s_addc_u32 s7, s7, 0
	s_mul_i32 s6, s15, s6
	s_add_u32 s0, s0, s6
	s_addc_u32 s14, 0, s7
	s_add_u32 s0, s45, s0
	s_cselect_b64 s[6:7], -1, 0
	s_cmp_lg_u64 s[6:7], 0
	s_addc_u32 s14, s15, s14
	v_mad_u64_u32 v[4:5], s[6:7], v6, s14, 0
	v_mul_hi_u32 v0, v6, s0
	v_lshl_add_u64 v[4:5], v[0:1], 0, v[4:5]
	v_mad_u64_u32 v[10:11], s[6:7], v7, s0, 0
	v_add_co_u32_e32 v0, vcc, v4, v10
	v_mad_u64_u32 v[8:9], s[6:7], v7, s14, 0
	s_nop 0
	v_addc_co_u32_e32 v0, vcc, v5, v11, vcc
	s_nop 1
	v_addc_co_u32_e32 v9, vcc, 0, v9, vcc
	v_lshl_add_u64 v[4:5], v[0:1], 0, v[8:9]
	v_mul_lo_u32 v0, s51, v4
	v_mul_lo_u32 v10, s50, v5
	v_mad_u64_u32 v[8:9], s[6:7], s50, v4, 0
	v_add3_u32 v0, v9, v10, v0
	v_sub_u32_e32 v9, v7, v0
	v_mov_b32_e32 v10, s51
	v_sub_co_u32_e32 v6, vcc, v6, v8
	s_nop 1
	v_subb_co_u32_e64 v8, s[6:7], v9, v10, vcc
	v_subrev_co_u32_e64 v9, s[6:7], s50, v6
	v_subb_co_u32_e32 v0, vcc, v7, v0, vcc
	s_nop 0
	v_subbrev_co_u32_e64 v8, s[6:7], 0, v8, s[6:7]
	v_cmp_le_u32_e64 s[6:7], s51, v8
	v_cmp_le_u32_e32 vcc, s51, v0
	s_nop 0
	v_cndmask_b32_e64 v10, 0, -1, s[6:7]
	v_cmp_le_u32_e64 s[6:7], s50, v9
	v_cndmask_b32_e64 v7, 0, -1, vcc
	v_cmp_le_u32_e32 vcc, s50, v6
	v_cndmask_b32_e64 v9, 0, -1, s[6:7]
	v_cmp_eq_u32_e64 s[6:7], s51, v8
	v_cndmask_b32_e64 v6, 0, -1, vcc
	v_cmp_eq_u32_e32 vcc, s51, v0
	v_cndmask_b32_e64 v12, v10, v9, s[6:7]
	v_lshl_add_u64 v[8:9], v[4:5], 0, 2
	v_lshl_add_u64 v[10:11], v[4:5], 0, 1
	v_cmp_ne_u32_e64 s[6:7], 0, v12
	v_cndmask_b32_e32 v0, v7, v6, vcc
	v_cmp_ne_u32_e32 vcc, 0, v0
	v_cndmask_b32_e64 v9, v11, v9, s[6:7]
	v_cndmask_b32_e64 v0, v10, v8, s[6:7]
	v_cndmask_b32_e32 v5, v5, v9, vcc
	v_cndmask_b32_e32 v4, v4, v0, vcc
